# adaLN GEMV tail: the bias element is loaded once per thread instead of four times; the three store-draining waits removed
# baseline (speedup 1.0000x reference)
.Lada_loop:
	global_load_dword v140, v[76:77], off nt
	v_lshl_add_u64 v[76:77], v[76:77], 0, s[0:1]
	global_load_dword v141, v[76:77], off nt
	v_lshl_add_u64 v[76:77], v[76:77], 0, s[0:1]
	global_load_dword v142, v[76:77], off nt
	v_lshl_add_u64 v[76:77], v[76:77], 0, s[0:1]
	global_load_dword v143, v[76:77], off nt
	v_lshl_add_u64 v[76:77], v[76:77], 0, s[0:1]
	global_load_dword v144, v[76:77], off nt
	v_lshl_add_u64 v[76:77], v[76:77], 0, s[0:1]
	global_load_dword v145, v[76:77], off nt
	v_lshl_add_u64 v[76:77], v[76:77], 0, s[0:1]
	global_load_dword v146, v[76:77], off nt
	v_lshl_add_u64 v[76:77], v[76:77], 0, s[0:1]
	global_load_dword v147, v[76:77], off nt
	v_lshl_add_u64 v[76:77], v[76:77], 0, s[0:1]
	global_load_dword v148, v[76:77], off nt
	v_lshl_add_u64 v[76:77], v[76:77], 0, s[0:1]
	global_load_dword v149, v[76:77], off nt
	v_lshl_add_u64 v[76:77], v[76:77], 0, s[0:1]
	global_load_dword v150, v[76:77], off nt
	v_lshl_add_u64 v[76:77], v[76:77], 0, s[0:1]
	global_load_dword v151, v[76:77], off nt
	v_lshl_add_u64 v[76:77], v[76:77], 0, s[0:1]
	global_load_dword v152, v[76:77], off nt
	v_lshl_add_u64 v[76:77], v[76:77], 0, s[0:1]
	global_load_dword v153, v[76:77], off nt
	v_lshl_add_u64 v[76:77], v[76:77], 0, s[0:1]
	global_load_dword v154, v[76:77], off nt
	v_lshl_add_u64 v[76:77], v[76:77], 0, s[0:1]
	global_load_dword v155, v[76:77], off nt
	v_lshl_add_u64 v[76:77], v[76:77], 0, s[0:1]
	s_waitcnt vmcnt(16)
	ds_read_b128 v[44:47], v32 offset:0
	ds_read_b128 v[48:51], v32 offset:16
	ds_read_b128 v[52:55], v32 offset:32
	ds_read_b128 v[56:59], v32 offset:48
	ds_read_b128 v[60:63], v32 offset:64
	ds_read_b128 v[64:67], v32 offset:80
	ds_read_b128 v[68:71], v32 offset:96
	ds_read_b128 v[72:75], v32 offset:112
	s_waitcnt lgkmcnt(4)
	v_pk_fma_f32 v[28:29], v[44:45], v[104:105], v[28:29] op_sel_hi:[1,0,1]
	v_pk_fma_f32 v[30:31], v[46:47], v[104:105], v[30:31] op_sel_hi:[1,0,1]
	v_pk_fma_f32 v[26:27], v[48:49], v[104:105], v[26:27] op_sel_hi:[1,0,1]
	v_pk_fma_f32 v[24:25], v[50:51], v[104:105], v[24:25] op_sel_hi:[1,0,1]
	v_pk_fma_f32 v[22:23], v[52:53], v[104:105], v[22:23] op_sel_hi:[1,0,1]
	v_pk_fma_f32 v[20:21], v[54:55], v[104:105], v[20:21] op_sel_hi:[1,0,1]
	v_pk_fma_f32 v[18:19], v[56:57], v[104:105], v[18:19] op_sel_hi:[1,0,1]
	v_pk_fma_f32 v[16:17], v[58:59], v[104:105], v[16:17] op_sel_hi:[1,0,1]
	ds_read_b128 v[44:47], v32 offset:128
	ds_read_b128 v[48:51], v32 offset:144
	ds_read_b128 v[52:55], v32 offset:160
	ds_read_b128 v[56:59], v32 offset:176
	s_waitcnt lgkmcnt(4)
	v_pk_fma_f32 v[28:29], v[60:61], v[104:105], v[28:29] op_sel:[0,1,0] op_sel_hi:[1,1,1]
	v_pk_fma_f32 v[30:31], v[62:63], v[104:105], v[30:31] op_sel:[0,1,0] op_sel_hi:[1,1,1]
	v_pk_fma_f32 v[26:27], v[64:65], v[104:105], v[26:27] op_sel:[0,1,0] op_sel_hi:[1,1,1]
	v_pk_fma_f32 v[24:25], v[66:67], v[104:105], v[24:25] op_sel:[0,1,0] op_sel_hi:[1,1,1]
	v_pk_fma_f32 v[22:23], v[68:69], v[104:105], v[22:23] op_sel:[0,1,0] op_sel_hi:[1,1,1]
	v_pk_fma_f32 v[20:21], v[70:71], v[104:105], v[20:21] op_sel:[0,1,0] op_sel_hi:[1,1,1]
	v_pk_fma_f32 v[18:19], v[72:73], v[104:105], v[18:19] op_sel:[0,1,0] op_sel_hi:[1,1,1]
	v_pk_fma_f32 v[16:17], v[74:75], v[104:105], v[16:17] op_sel:[0,1,0] op_sel_hi:[1,1,1]
	ds_read_b128 v[60:63], v32 offset:192
	ds_read_b128 v[64:67], v32 offset:208
	ds_read_b128 v[68:71], v32 offset:224
	ds_read_b128 v[72:75], v32 offset:240
	s_waitcnt lgkmcnt(4)
	v_pk_fma_f32 v[28:29], v[44:45], v[106:107], v[28:29] op_sel_hi:[1,0,1]
	v_pk_fma_f32 v[30:31], v[46:47], v[106:107], v[30:31] op_sel_hi:[1,0,1]
	v_pk_fma_f32 v[26:27], v[48:49], v[106:107], v[26:27] op_sel_hi:[1,0,1]
	v_pk_fma_f32 v[24:25], v[50:51], v[106:107], v[24:25] op_sel_hi:[1,0,1]
	v_pk_fma_f32 v[22:23], v[52:53], v[106:107], v[22:23] op_sel_hi:[1,0,1]
	v_pk_fma_f32 v[20:21], v[54:55], v[106:107], v[20:21] op_sel_hi:[1,0,1]
	v_pk_fma_f32 v[18:19], v[56:57], v[106:107], v[18:19] op_sel_hi:[1,0,1]
	v_pk_fma_f32 v[16:17], v[58:59], v[106:107], v[16:17] op_sel_hi:[1,0,1]
	ds_read_b128 v[44:47], v32 offset:256
	ds_read_b128 v[48:51], v32 offset:272
	ds_read_b128 v[52:55], v32 offset:288
	ds_read_b128 v[56:59], v32 offset:304
	s_waitcnt lgkmcnt(4)
	v_pk_fma_f32 v[28:29], v[60:61], v[106:107], v[28:29] op_sel:[0,1,0] op_sel_hi:[1,1,1]
	v_pk_fma_f32 v[30:31], v[62:63], v[106:107], v[30:31] op_sel:[0,1,0] op_sel_hi:[1,1,1]
	v_pk_fma_f32 v[26:27], v[64:65], v[106:107], v[26:27] op_sel:[0,1,0] op_sel_hi:[1,1,1]
	v_pk_fma_f32 v[24:25], v[66:67], v[106:107], v[24:25] op_sel:[0,1,0] op_sel_hi:[1,1,1]
	v_pk_fma_f32 v[22:23], v[68:69], v[106:107], v[22:23] op_sel:[0,1,0] op_sel_hi:[1,1,1]
	v_pk_fma_f32 v[20:21], v[70:71], v[106:107], v[20:21] op_sel:[0,1,0] op_sel_hi:[1,1,1]
	v_pk_fma_f32 v[18:19], v[72:73], v[106:107], v[18:19] op_sel:[0,1,0] op_sel_hi:[1,1,1]
	v_pk_fma_f32 v[16:17], v[74:75], v[106:107], v[16:17] op_sel:[0,1,0] op_sel_hi:[1,1,1]
	ds_read_b128 v[60:63], v32 offset:320
	ds_read_b128 v[64:67], v32 offset:336
	ds_read_b128 v[68:71], v32 offset:352
	ds_read_b128 v[72:75], v32 offset:368
	s_waitcnt lgkmcnt(4)
	v_pk_fma_f32 v[28:29], v[44:45], v[108:109], v[28:29] op_sel_hi:[1,0,1]
	v_pk_fma_f32 v[30:31], v[46:47], v[108:109], v[30:31] op_sel_hi:[1,0,1]
	v_pk_fma_f32 v[26:27], v[48:49], v[108:109], v[26:27] op_sel_hi:[1,0,1]
	v_pk_fma_f32 v[24:25], v[50:51], v[108:109], v[24:25] op_sel_hi:[1,0,1]
	v_pk_fma_f32 v[22:23], v[52:53], v[108:109], v[22:23] op_sel_hi:[1,0,1]
	v_pk_fma_f32 v[20:21], v[54:55], v[108:109], v[20:21] op_sel_hi:[1,0,1]
	v_pk_fma_f32 v[18:19], v[56:57], v[108:109], v[18:19] op_sel_hi:[1,0,1]
	v_pk_fma_f32 v[16:17], v[58:59], v[108:109], v[16:17] op_sel_hi:[1,0,1]
	ds_read_b128 v[44:47], v32 offset:384
	ds_read_b128 v[48:51], v32 offset:400
	ds_read_b128 v[52:55], v32 offset:416
	ds_read_b128 v[56:59], v32 offset:432
	s_waitcnt lgkmcnt(4)
	v_pk_fma_f32 v[28:29], v[60:61], v[108:109], v[28:29] op_sel:[0,1,0] op_sel_hi:[1,1,1]
	v_pk_fma_f32 v[30:31], v[62:63], v[108:109], v[30:31] op_sel:[0,1,0] op_sel_hi:[1,1,1]
	v_pk_fma_f32 v[26:27], v[64:65], v[108:109], v[26:27] op_sel:[0,1,0] op_sel_hi:[1,1,1]
	v_pk_fma_f32 v[24:25], v[66:67], v[108:109], v[24:25] op_sel:[0,1,0] op_sel_hi:[1,1,1]
	v_pk_fma_f32 v[22:23], v[68:69], v[108:109], v[22:23] op_sel:[0,1,0] op_sel_hi:[1,1,1]
	v_pk_fma_f32 v[20:21], v[70:71], v[108:109], v[20:21] op_sel:[0,1,0] op_sel_hi:[1,1,1]
	v_pk_fma_f32 v[18:19], v[72:73], v[108:109], v[18:19] op_sel:[0,1,0] op_sel_hi:[1,1,1]
	v_pk_fma_f32 v[16:17], v[74:75], v[108:109], v[16:17] op_sel:[0,1,0] op_sel_hi:[1,1,1]
	ds_read_b128 v[60:63], v32 offset:448
	ds_read_b128 v[64:67], v32 offset:464
	ds_read_b128 v[68:71], v32 offset:480
	ds_read_b128 v[72:75], v32 offset:496
	s_waitcnt lgkmcnt(4)
	v_pk_fma_f32 v[28:29], v[44:45], v[110:111], v[28:29] op_sel_hi:[1,0,1]
	v_pk_fma_f32 v[30:31], v[46:47], v[110:111], v[30:31] op_sel_hi:[1,0,1]
	v_pk_fma_f32 v[26:27], v[48:49], v[110:111], v[26:27] op_sel_hi:[1,0,1]
	v_pk_fma_f32 v[24:25], v[50:51], v[110:111], v[24:25] op_sel_hi:[1,0,1]
	v_pk_fma_f32 v[22:23], v[52:53], v[110:111], v[22:23] op_sel_hi:[1,0,1]
	v_pk_fma_f32 v[20:21], v[54:55], v[110:111], v[20:21] op_sel_hi:[1,0,1]
	v_pk_fma_f32 v[18:19], v[56:57], v[110:111], v[18:19] op_sel_hi:[1,0,1]
	v_pk_fma_f32 v[16:17], v[58:59], v[110:111], v[16:17] op_sel_hi:[1,0,1]
	ds_read_b128 v[44:47], v32 offset:512
	ds_read_b128 v[48:51], v32 offset:528
	ds_read_b128 v[52:55], v32 offset:544
	ds_read_b128 v[56:59], v32 offset:560
	s_waitcnt lgkmcnt(4)
	v_pk_fma_f32 v[28:29], v[60:61], v[110:111], v[28:29] op_sel:[0,1,0] op_sel_hi:[1,1,1]
	v_pk_fma_f32 v[30:31], v[62:63], v[110:111], v[30:31] op_sel:[0,1,0] op_sel_hi:[1,1,1]
	v_pk_fma_f32 v[26:27], v[64:65], v[110:111], v[26:27] op_sel:[0,1,0] op_sel_hi:[1,1,1]
	v_pk_fma_f32 v[24:25], v[66:67], v[110:111], v[24:25] op_sel:[0,1,0] op_sel_hi:[1,1,1]
	v_pk_fma_f32 v[22:23], v[68:69], v[110:111], v[22:23] op_sel:[0,1,0] op_sel_hi:[1,1,1]
	v_pk_fma_f32 v[20:21], v[70:71], v[110:111], v[20:21] op_sel:[0,1,0] op_sel_hi:[1,1,1]
	v_pk_fma_f32 v[18:19], v[72:73], v[110:111], v[18:19] op_sel:[0,1,0] op_sel_hi:[1,1,1]
	v_pk_fma_f32 v[16:17], v[74:75], v[110:111], v[16:17] op_sel:[0,1,0] op_sel_hi:[1,1,1]
	ds_read_b128 v[60:63], v32 offset:576
	ds_read_b128 v[64:67], v32 offset:592
	ds_read_b128 v[68:71], v32 offset:608
	ds_read_b128 v[72:75], v32 offset:624
	s_waitcnt lgkmcnt(4)
	v_pk_fma_f32 v[28:29], v[44:45], v[112:113], v[28:29] op_sel_hi:[1,0,1]
	v_pk_fma_f32 v[30:31], v[46:47], v[112:113], v[30:31] op_sel_hi:[1,0,1]
	v_pk_fma_f32 v[26:27], v[48:49], v[112:113], v[26:27] op_sel_hi:[1,0,1]
	v_pk_fma_f32 v[24:25], v[50:51], v[112:113], v[24:25] op_sel_hi:[1,0,1]
	v_pk_fma_f32 v[22:23], v[52:53], v[112:113], v[22:23] op_sel_hi:[1,0,1]
	v_pk_fma_f32 v[20:21], v[54:55], v[112:113], v[20:21] op_sel_hi:[1,0,1]
	v_pk_fma_f32 v[18:19], v[56:57], v[112:113], v[18:19] op_sel_hi:[1,0,1]
	v_pk_fma_f32 v[16:17], v[58:59], v[112:113], v[16:17] op_sel_hi:[1,0,1]
	ds_read_b128 v[44:47], v32 offset:640
	ds_read_b128 v[48:51], v32 offset:656
	ds_read_b128 v[52:55], v32 offset:672
	ds_read_b128 v[56:59], v32 offset:688
	s_waitcnt lgkmcnt(4)
	v_pk_fma_f32 v[28:29], v[60:61], v[112:113], v[28:29] op_sel:[0,1,0] op_sel_hi:[1,1,1]
	v_pk_fma_f32 v[30:31], v[62:63], v[112:113], v[30:31] op_sel:[0,1,0] op_sel_hi:[1,1,1]
	v_pk_fma_f32 v[26:27], v[64:65], v[112:113], v[26:27] op_sel:[0,1,0] op_sel_hi:[1,1,1]
	v_pk_fma_f32 v[24:25], v[66:67], v[112:113], v[24:25] op_sel:[0,1,0] op_sel_hi:[1,1,1]
	v_pk_fma_f32 v[22:23], v[68:69], v[112:113], v[22:23] op_sel:[0,1,0] op_sel_hi:[1,1,1]
	v_pk_fma_f32 v[20:21], v[70:71], v[112:113], v[20:21] op_sel:[0,1,0] op_sel_hi:[1,1,1]
	v_pk_fma_f32 v[18:19], v[72:73], v[112:113], v[18:19] op_sel:[0,1,0] op_sel_hi:[1,1,1]
	v_pk_fma_f32 v[16:17], v[74:75], v[112:113], v[16:17] op_sel:[0,1,0] op_sel_hi:[1,1,1]
	ds_read_b128 v[60:63], v32 offset:704
	ds_read_b128 v[64:67], v32 offset:720
	ds_read_b128 v[68:71], v32 offset:736
	ds_read_b128 v[72:75], v32 offset:752
	s_waitcnt lgkmcnt(4)
	v_pk_fma_f32 v[28:29], v[44:45], v[114:115], v[28:29] op_sel_hi:[1,0,1]
	v_pk_fma_f32 v[30:31], v[46:47], v[114:115], v[30:31] op_sel_hi:[1,0,1]
	v_pk_fma_f32 v[26:27], v[48:49], v[114:115], v[26:27] op_sel_hi:[1,0,1]
	v_pk_fma_f32 v[24:25], v[50:51], v[114:115], v[24:25] op_sel_hi:[1,0,1]
	v_pk_fma_f32 v[22:23], v[52:53], v[114:115], v[22:23] op_sel_hi:[1,0,1]
	v_pk_fma_f32 v[20:21], v[54:55], v[114:115], v[20:21] op_sel_hi:[1,0,1]
	v_pk_fma_f32 v[18:19], v[56:57], v[114:115], v[18:19] op_sel_hi:[1,0,1]
	v_pk_fma_f32 v[16:17], v[58:59], v[114:115], v[16:17] op_sel_hi:[1,0,1]
	ds_read_b128 v[44:47], v32 offset:768
	ds_read_b128 v[48:51], v32 offset:784
	ds_read_b128 v[52:55], v32 offset:800
	ds_read_b128 v[56:59], v32 offset:816
	s_waitcnt lgkmcnt(4)
	v_pk_fma_f32 v[28:29], v[60:61], v[114:115], v[28:29] op_sel:[0,1,0] op_sel_hi:[1,1,1]
	v_pk_fma_f32 v[30:31], v[62:63], v[114:115], v[30:31] op_sel:[0,1,0] op_sel_hi:[1,1,1]
	v_pk_fma_f32 v[26:27], v[64:65], v[114:115], v[26:27] op_sel:[0,1,0] op_sel_hi:[1,1,1]
	v_pk_fma_f32 v[24:25], v[66:67], v[114:115], v[24:25] op_sel:[0,1,0] op_sel_hi:[1,1,1]
	v_pk_fma_f32 v[22:23], v[68:69], v[114:115], v[22:23] op_sel:[0,1,0] op_sel_hi:[1,1,1]
	v_pk_fma_f32 v[20:21], v[70:71], v[114:115], v[20:21] op_sel:[0,1,0] op_sel_hi:[1,1,1]
	v_pk_fma_f32 v[18:19], v[72:73], v[114:115], v[18:19] op_sel:[0,1,0] op_sel_hi:[1,1,1]
	v_pk_fma_f32 v[16:17], v[74:75], v[114:115], v[16:17] op_sel:[0,1,0] op_sel_hi:[1,1,1]
	ds_read_b128 v[60:63], v32 offset:832
	ds_read_b128 v[64:67], v32 offset:848
	ds_read_b128 v[68:71], v32 offset:864
	ds_read_b128 v[72:75], v32 offset:880
	s_waitcnt lgkmcnt(4)
	v_pk_fma_f32 v[28:29], v[44:45], v[116:117], v[28:29] op_sel_hi:[1,0,1]
	v_pk_fma_f32 v[30:31], v[46:47], v[116:117], v[30:31] op_sel_hi:[1,0,1]
	v_pk_fma_f32 v[26:27], v[48:49], v[116:117], v[26:27] op_sel_hi:[1,0,1]
	v_pk_fma_f32 v[24:25], v[50:51], v[116:117], v[24:25] op_sel_hi:[1,0,1]
	v_pk_fma_f32 v[22:23], v[52:53], v[116:117], v[22:23] op_sel_hi:[1,0,1]
	v_pk_fma_f32 v[20:21], v[54:55], v[116:117], v[20:21] op_sel_hi:[1,0,1]
	v_pk_fma_f32 v[18:19], v[56:57], v[116:117], v[18:19] op_sel_hi:[1,0,1]
	v_pk_fma_f32 v[16:17], v[58:59], v[116:117], v[16:17] op_sel_hi:[1,0,1]
	ds_read_b128 v[44:47], v32 offset:896
	ds_read_b128 v[48:51], v32 offset:912
	ds_read_b128 v[52:55], v32 offset:928
	ds_read_b128 v[56:59], v32 offset:944
	s_waitcnt lgkmcnt(4)
	v_pk_fma_f32 v[28:29], v[60:61], v[116:117], v[28:29] op_sel:[0,1,0] op_sel_hi:[1,1,1]
	v_pk_fma_f32 v[30:31], v[62:63], v[116:117], v[30:31] op_sel:[0,1,0] op_sel_hi:[1,1,1]
	v_pk_fma_f32 v[26:27], v[64:65], v[116:117], v[26:27] op_sel:[0,1,0] op_sel_hi:[1,1,1]
	v_pk_fma_f32 v[24:25], v[66:67], v[116:117], v[24:25] op_sel:[0,1,0] op_sel_hi:[1,1,1]
	v_pk_fma_f32 v[22:23], v[68:69], v[116:117], v[22:23] op_sel:[0,1,0] op_sel_hi:[1,1,1]
	v_pk_fma_f32 v[20:21], v[70:71], v[116:117], v[20:21] op_sel:[0,1,0] op_sel_hi:[1,1,1]
	v_pk_fma_f32 v[18:19], v[72:73], v[116:117], v[18:19] op_sel:[0,1,0] op_sel_hi:[1,1,1]
	v_pk_fma_f32 v[16:17], v[74:75], v[116:117], v[16:17] op_sel:[0,1,0] op_sel_hi:[1,1,1]
	ds_read_b128 v[60:63], v32 offset:960
	ds_read_b128 v[64:67], v32 offset:976
	ds_read_b128 v[68:71], v32 offset:992
	ds_read_b128 v[72:75], v32 offset:1008
	s_waitcnt lgkmcnt(4)
	v_pk_fma_f32 v[28:29], v[44:45], v[118:119], v[28:29] op_sel_hi:[1,0,1]
	v_pk_fma_f32 v[30:31], v[46:47], v[118:119], v[30:31] op_sel_hi:[1,0,1]
	v_pk_fma_f32 v[26:27], v[48:49], v[118:119], v[26:27] op_sel_hi:[1,0,1]
	v_pk_fma_f32 v[24:25], v[50:51], v[118:119], v[24:25] op_sel_hi:[1,0,1]
	v_pk_fma_f32 v[22:23], v[52:53], v[118:119], v[22:23] op_sel_hi:[1,0,1]
	v_pk_fma_f32 v[20:21], v[54:55], v[118:119], v[20:21] op_sel_hi:[1,0,1]
	v_pk_fma_f32 v[18:19], v[56:57], v[118:119], v[18:19] op_sel_hi:[1,0,1]
	v_pk_fma_f32 v[16:17], v[58:59], v[118:119], v[16:17] op_sel_hi:[1,0,1]
	s_waitcnt lgkmcnt(0)
	v_pk_fma_f32 v[28:29], v[60:61], v[118:119], v[28:29] op_sel:[0,1,0] op_sel_hi:[1,1,1]
	v_pk_fma_f32 v[30:31], v[62:63], v[118:119], v[30:31] op_sel:[0,1,0] op_sel_hi:[1,1,1]
	v_pk_fma_f32 v[26:27], v[64:65], v[118:119], v[26:27] op_sel:[0,1,0] op_sel_hi:[1,1,1]
	v_pk_fma_f32 v[24:25], v[66:67], v[118:119], v[24:25] op_sel:[0,1,0] op_sel_hi:[1,1,1]
	v_pk_fma_f32 v[22:23], v[68:69], v[118:119], v[22:23] op_sel:[0,1,0] op_sel_hi:[1,1,1]
	v_pk_fma_f32 v[20:21], v[70:71], v[118:119], v[20:21] op_sel:[0,1,0] op_sel_hi:[1,1,1]
	v_pk_fma_f32 v[18:19], v[72:73], v[118:119], v[18:19] op_sel:[0,1,0] op_sel_hi:[1,1,1]
	v_pk_fma_f32 v[16:17], v[74:75], v[118:119], v[16:17] op_sel:[0,1,0] op_sel_hi:[1,1,1]
	v_add_u32_e32 v32, 0x400, v32
	global_load_dword v104, v[76:77], off nt
	v_lshl_add_u64 v[76:77], v[76:77], 0, s[0:1]
	global_load_dword v105, v[76:77], off nt
	v_lshl_add_u64 v[76:77], v[76:77], 0, s[0:1]
	global_load_dword v106, v[76:77], off nt
	v_lshl_add_u64 v[76:77], v[76:77], 0, s[0:1]
	global_load_dword v107, v[76:77], off nt
	v_lshl_add_u64 v[76:77], v[76:77], 0, s[0:1]
	global_load_dword v108, v[76:77], off nt
	v_lshl_add_u64 v[76:77], v[76:77], 0, s[0:1]
	global_load_dword v109, v[76:77], off nt
	v_lshl_add_u64 v[76:77], v[76:77], 0, s[0:1]
	global_load_dword v110, v[76:77], off nt
	v_lshl_add_u64 v[76:77], v[76:77], 0, s[0:1]
	global_load_dword v111, v[76:77], off nt
	v_lshl_add_u64 v[76:77], v[76:77], 0, s[0:1]
	global_load_dword v112, v[76:77], off nt
	v_lshl_add_u64 v[76:77], v[76:77], 0, s[0:1]
	global_load_dword v113, v[76:77], off nt
	v_lshl_add_u64 v[76:77], v[76:77], 0, s[0:1]
	global_load_dword v114, v[76:77], off nt
	v_lshl_add_u64 v[76:77], v[76:77], 0, s[0:1]
	global_load_dword v115, v[76:77], off nt
	v_lshl_add_u64 v[76:77], v[76:77], 0, s[0:1]
	global_load_dword v116, v[76:77], off nt
	v_lshl_add_u64 v[76:77], v[76:77], 0, s[0:1]
	global_load_dword v117, v[76:77], off nt
	v_lshl_add_u64 v[76:77], v[76:77], 0, s[0:1]
	global_load_dword v118, v[76:77], off nt
	v_lshl_add_u64 v[76:77], v[76:77], 0, s[0:1]
	global_load_dword v119, v[76:77], off nt
	v_lshl_add_u64 v[76:77], v[76:77], 0, s[0:1]
	s_waitcnt vmcnt(16)
	ds_read_b128 v[44:47], v32 offset:0
	ds_read_b128 v[48:51], v32 offset:16
	ds_read_b128 v[52:55], v32 offset:32
	ds_read_b128 v[56:59], v32 offset:48
	ds_read_b128 v[60:63], v32 offset:64
	ds_read_b128 v[64:67], v32 offset:80
	ds_read_b128 v[68:71], v32 offset:96
	ds_read_b128 v[72:75], v32 offset:112
	s_waitcnt lgkmcnt(4)
	v_pk_fma_f32 v[28:29], v[44:45], v[140:141], v[28:29] op_sel_hi:[1,0,1]
	v_pk_fma_f32 v[30:31], v[46:47], v[140:141], v[30:31] op_sel_hi:[1,0,1]
	v_pk_fma_f32 v[26:27], v[48:49], v[140:141], v[26:27] op_sel_hi:[1,0,1]
	v_pk_fma_f32 v[24:25], v[50:51], v[140:141], v[24:25] op_sel_hi:[1,0,1]
	v_pk_fma_f32 v[22:23], v[52:53], v[140:141], v[22:23] op_sel_hi:[1,0,1]
	v_pk_fma_f32 v[20:21], v[54:55], v[140:141], v[20:21] op_sel_hi:[1,0,1]
	v_pk_fma_f32 v[18:19], v[56:57], v[140:141], v[18:19] op_sel_hi:[1,0,1]
	v_pk_fma_f32 v[16:17], v[58:59], v[140:141], v[16:17] op_sel_hi:[1,0,1]
	ds_read_b128 v[44:47], v32 offset:128
	ds_read_b128 v[48:51], v32 offset:144
	ds_read_b128 v[52:55], v32 offset:160
	ds_read_b128 v[56:59], v32 offset:176
	s_waitcnt lgkmcnt(4)
	v_pk_fma_f32 v[28:29], v[60:61], v[140:141], v[28:29] op_sel:[0,1,0] op_sel_hi:[1,1,1]
	v_pk_fma_f32 v[30:31], v[62:63], v[140:141], v[30:31] op_sel:[0,1,0] op_sel_hi:[1,1,1]
	v_pk_fma_f32 v[26:27], v[64:65], v[140:141], v[26:27] op_sel:[0,1,0] op_sel_hi:[1,1,1]
	v_pk_fma_f32 v[24:25], v[66:67], v[140:141], v[24:25] op_sel:[0,1,0] op_sel_hi:[1,1,1]
	v_pk_fma_f32 v[22:23], v[68:69], v[140:141], v[22:23] op_sel:[0,1,0] op_sel_hi:[1,1,1]
	v_pk_fma_f32 v[20:21], v[70:71], v[140:141], v[20:21] op_sel:[0,1,0] op_sel_hi:[1,1,1]
	v_pk_fma_f32 v[18:19], v[72:73], v[140:141], v[18:19] op_sel:[0,1,0] op_sel_hi:[1,1,1]
	v_pk_fma_f32 v[16:17], v[74:75], v[140:141], v[16:17] op_sel:[0,1,0] op_sel_hi:[1,1,1]
	ds_read_b128 v[60:63], v32 offset:192
	ds_read_b128 v[64:67], v32 offset:208
	ds_read_b128 v[68:71], v32 offset:224
	ds_read_b128 v[72:75], v32 offset:240
	s_waitcnt lgkmcnt(4)
	v_pk_fma_f32 v[28:29], v[44:45], v[142:143], v[28:29] op_sel_hi:[1,0,1]
	v_pk_fma_f32 v[30:31], v[46:47], v[142:143], v[30:31] op_sel_hi:[1,0,1]
	v_pk_fma_f32 v[26:27], v[48:49], v[142:143], v[26:27] op_sel_hi:[1,0,1]
	v_pk_fma_f32 v[24:25], v[50:51], v[142:143], v[24:25] op_sel_hi:[1,0,1]
	v_pk_fma_f32 v[22:23], v[52:53], v[142:143], v[22:23] op_sel_hi:[1,0,1]
	v_pk_fma_f32 v[20:21], v[54:55], v[142:143], v[20:21] op_sel_hi:[1,0,1]
	v_pk_fma_f32 v[18:19], v[56:57], v[142:143], v[18:19] op_sel_hi:[1,0,1]
	v_pk_fma_f32 v[16:17], v[58:59], v[142:143], v[16:17] op_sel_hi:[1,0,1]
	ds_read_b128 v[44:47], v32 offset:256
	ds_read_b128 v[48:51], v32 offset:272
	ds_read_b128 v[52:55], v32 offset:288
	ds_read_b128 v[56:59], v32 offset:304
	s_waitcnt lgkmcnt(4)
	v_pk_fma_f32 v[28:29], v[60:61], v[142:143], v[28:29] op_sel:[0,1,0] op_sel_hi:[1,1,1]
	v_pk_fma_f32 v[30:31], v[62:63], v[142:143], v[30:31] op_sel:[0,1,0] op_sel_hi:[1,1,1]
	v_pk_fma_f32 v[26:27], v[64:65], v[142:143], v[26:27] op_sel:[0,1,0] op_sel_hi:[1,1,1]
	v_pk_fma_f32 v[24:25], v[66:67], v[142:143], v[24:25] op_sel:[0,1,0] op_sel_hi:[1,1,1]
	v_pk_fma_f32 v[22:23], v[68:69], v[142:143], v[22:23] op_sel:[0,1,0] op_sel_hi:[1,1,1]
	v_pk_fma_f32 v[20:21], v[70:71], v[142:143], v[20:21] op_sel:[0,1,0] op_sel_hi:[1,1,1]
	v_pk_fma_f32 v[18:19], v[72:73], v[142:143], v[18:19] op_sel:[0,1,0] op_sel_hi:[1,1,1]
	v_pk_fma_f32 v[16:17], v[74:75], v[142:143], v[16:17] op_sel:[0,1,0] op_sel_hi:[1,1,1]
	ds_read_b128 v[60:63], v32 offset:320
	ds_read_b128 v[64:67], v32 offset:336
	ds_read_b128 v[68:71], v32 offset:352
	ds_read_b128 v[72:75], v32 offset:368
	s_waitcnt lgkmcnt(4)
	v_pk_fma_f32 v[28:29], v[44:45], v[144:145], v[28:29] op_sel_hi:[1,0,1]
	v_pk_fma_f32 v[30:31], v[46:47], v[144:145], v[30:31] op_sel_hi:[1,0,1]
	v_pk_fma_f32 v[26:27], v[48:49], v[144:145], v[26:27] op_sel_hi:[1,0,1]
	v_pk_fma_f32 v[24:25], v[50:51], v[144:145], v[24:25] op_sel_hi:[1,0,1]
	v_pk_fma_f32 v[22:23], v[52:53], v[144:145], v[22:23] op_sel_hi:[1,0,1]
	v_pk_fma_f32 v[20:21], v[54:55], v[144:145], v[20:21] op_sel_hi:[1,0,1]
	v_pk_fma_f32 v[18:19], v[56:57], v[144:145], v[18:19] op_sel_hi:[1,0,1]
	v_pk_fma_f32 v[16:17], v[58:59], v[144:145], v[16:17] op_sel_hi:[1,0,1]
	ds_read_b128 v[44:47], v32 offset:384
	ds_read_b128 v[48:51], v32 offset:400
	ds_read_b128 v[52:55], v32 offset:416
	ds_read_b128 v[56:59], v32 offset:432
	s_waitcnt lgkmcnt(4)
	v_pk_fma_f32 v[28:29], v[60:61], v[144:145], v[28:29] op_sel:[0,1,0] op_sel_hi:[1,1,1]
	v_pk_fma_f32 v[30:31], v[62:63], v[144:145], v[30:31] op_sel:[0,1,0] op_sel_hi:[1,1,1]
	v_pk_fma_f32 v[26:27], v[64:65], v[144:145], v[26:27] op_sel:[0,1,0] op_sel_hi:[1,1,1]
	v_pk_fma_f32 v[24:25], v[66:67], v[144:145], v[24:25] op_sel:[0,1,0] op_sel_hi:[1,1,1]
	v_pk_fma_f32 v[22:23], v[68:69], v[144:145], v[22:23] op_sel:[0,1,0] op_sel_hi:[1,1,1]
	v_pk_fma_f32 v[20:21], v[70:71], v[144:145], v[20:21] op_sel:[0,1,0] op_sel_hi:[1,1,1]
	v_pk_fma_f32 v[18:19], v[72:73], v[144:145], v[18:19] op_sel:[0,1,0] op_sel_hi:[1,1,1]
	v_pk_fma_f32 v[16:17], v[74:75], v[144:145], v[16:17] op_sel:[0,1,0] op_sel_hi:[1,1,1]
	ds_read_b128 v[60:63], v32 offset:448
	ds_read_b128 v[64:67], v32 offset:464
	ds_read_b128 v[68:71], v32 offset:480
	ds_read_b128 v[72:75], v32 offset:496
	s_waitcnt lgkmcnt(4)
	v_pk_fma_f32 v[28:29], v[44:45], v[146:147], v[28:29] op_sel_hi:[1,0,1]
	v_pk_fma_f32 v[30:31], v[46:47], v[146:147], v[30:31] op_sel_hi:[1,0,1]
	v_pk_fma_f32 v[26:27], v[48:49], v[146:147], v[26:27] op_sel_hi:[1,0,1]
	v_pk_fma_f32 v[24:25], v[50:51], v[146:147], v[24:25] op_sel_hi:[1,0,1]
	v_pk_fma_f32 v[22:23], v[52:53], v[146:147], v[22:23] op_sel_hi:[1,0,1]
	v_pk_fma_f32 v[20:21], v[54:55], v[146:147], v[20:21] op_sel_hi:[1,0,1]
	v_pk_fma_f32 v[18:19], v[56:57], v[146:147], v[18:19] op_sel_hi:[1,0,1]
	v_pk_fma_f32 v[16:17], v[58:59], v[146:147], v[16:17] op_sel_hi:[1,0,1]
	ds_read_b128 v[44:47], v32 offset:512
	ds_read_b128 v[48:51], v32 offset:528
	ds_read_b128 v[52:55], v32 offset:544
	ds_read_b128 v[56:59], v32 offset:560
	s_waitcnt lgkmcnt(4)
	v_pk_fma_f32 v[28:29], v[60:61], v[146:147], v[28:29] op_sel:[0,1,0] op_sel_hi:[1,1,1]
	v_pk_fma_f32 v[30:31], v[62:63], v[146:147], v[30:31] op_sel:[0,1,0] op_sel_hi:[1,1,1]
	v_pk_fma_f32 v[26:27], v[64:65], v[146:147], v[26:27] op_sel:[0,1,0] op_sel_hi:[1,1,1]
	v_pk_fma_f32 v[24:25], v[66:67], v[146:147], v[24:25] op_sel:[0,1,0] op_sel_hi:[1,1,1]
	v_pk_fma_f32 v[22:23], v[68:69], v[146:147], v[22:23] op_sel:[0,1,0] op_sel_hi:[1,1,1]
	v_pk_fma_f32 v[20:21], v[70:71], v[146:147], v[20:21] op_sel:[0,1,0] op_sel_hi:[1,1,1]
	v_pk_fma_f32 v[18:19], v[72:73], v[146:147], v[18:19] op_sel:[0,1,0] op_sel_hi:[1,1,1]
	v_pk_fma_f32 v[16:17], v[74:75], v[146:147], v[16:17] op_sel:[0,1,0] op_sel_hi:[1,1,1]
	ds_read_b128 v[60:63], v32 offset:576
	ds_read_b128 v[64:67], v32 offset:592
	ds_read_b128 v[68:71], v32 offset:608
	ds_read_b128 v[72:75], v32 offset:624
	s_waitcnt lgkmcnt(4)
	v_pk_fma_f32 v[28:29], v[44:45], v[148:149], v[28:29] op_sel_hi:[1,0,1]
	v_pk_fma_f32 v[30:31], v[46:47], v[148:149], v[30:31] op_sel_hi:[1,0,1]
	v_pk_fma_f32 v[26:27], v[48:49], v[148:149], v[26:27] op_sel_hi:[1,0,1]
	v_pk_fma_f32 v[24:25], v[50:51], v[148:149], v[24:25] op_sel_hi:[1,0,1]
	v_pk_fma_f32 v[22:23], v[52:53], v[148:149], v[22:23] op_sel_hi:[1,0,1]
	v_pk_fma_f32 v[20:21], v[54:55], v[148:149], v[20:21] op_sel_hi:[1,0,1]
	v_pk_fma_f32 v[18:19], v[56:57], v[148:149], v[18:19] op_sel_hi:[1,0,1]
	v_pk_fma_f32 v[16:17], v[58:59], v[148:149], v[16:17] op_sel_hi:[1,0,1]
	ds_read_b128 v[44:47], v32 offset:640
	ds_read_b128 v[48:51], v32 offset:656
	ds_read_b128 v[52:55], v32 offset:672
	ds_read_b128 v[56:59], v32 offset:688
	s_waitcnt lgkmcnt(4)
	v_pk_fma_f32 v[28:29], v[60:61], v[148:149], v[28:29] op_sel:[0,1,0] op_sel_hi:[1,1,1]
	v_pk_fma_f32 v[30:31], v[62:63], v[148:149], v[30:31] op_sel:[0,1,0] op_sel_hi:[1,1,1]
	v_pk_fma_f32 v[26:27], v[64:65], v[148:149], v[26:27] op_sel:[0,1,0] op_sel_hi:[1,1,1]
	v_pk_fma_f32 v[24:25], v[66:67], v[148:149], v[24:25] op_sel:[0,1,0] op_sel_hi:[1,1,1]
	v_pk_fma_f32 v[22:23], v[68:69], v[148:149], v[22:23] op_sel:[0,1,0] op_sel_hi:[1,1,1]
	v_pk_fma_f32 v[20:21], v[70:71], v[148:149], v[20:21] op_sel:[0,1,0] op_sel_hi:[1,1,1]
	v_pk_fma_f32 v[18:19], v[72:73], v[148:149], v[18:19] op_sel:[0,1,0] op_sel_hi:[1,1,1]
	v_pk_fma_f32 v[16:17], v[74:75], v[148:149], v[16:17] op_sel:[0,1,0] op_sel_hi:[1,1,1]
	ds_read_b128 v[60:63], v32 offset:704
	ds_read_b128 v[64:67], v32 offset:720
	ds_read_b128 v[68:71], v32 offset:736
	ds_read_b128 v[72:75], v32 offset:752
	s_waitcnt lgkmcnt(4)
	v_pk_fma_f32 v[28:29], v[44:45], v[150:151], v[28:29] op_sel_hi:[1,0,1]
	v_pk_fma_f32 v[30:31], v[46:47], v[150:151], v[30:31] op_sel_hi:[1,0,1]
	v_pk_fma_f32 v[26:27], v[48:49], v[150:151], v[26:27] op_sel_hi:[1,0,1]
	v_pk_fma_f32 v[24:25], v[50:51], v[150:151], v[24:25] op_sel_hi:[1,0,1]
	v_pk_fma_f32 v[22:23], v[52:53], v[150:151], v[22:23] op_sel_hi:[1,0,1]
	v_pk_fma_f32 v[20:21], v[54:55], v[150:151], v[20:21] op_sel_hi:[1,0,1]
	v_pk_fma_f32 v[18:19], v[56:57], v[150:151], v[18:19] op_sel_hi:[1,0,1]
	v_pk_fma_f32 v[16:17], v[58:59], v[150:151], v[16:17] op_sel_hi:[1,0,1]
	ds_read_b128 v[44:47], v32 offset:768
	ds_read_b128 v[48:51], v32 offset:784
	ds_read_b128 v[52:55], v32 offset:800
	ds_read_b128 v[56:59], v32 offset:816
	s_waitcnt lgkmcnt(4)
	v_pk_fma_f32 v[28:29], v[60:61], v[150:151], v[28:29] op_sel:[0,1,0] op_sel_hi:[1,1,1]
	v_pk_fma_f32 v[30:31], v[62:63], v[150:151], v[30:31] op_sel:[0,1,0] op_sel_hi:[1,1,1]
	v_pk_fma_f32 v[26:27], v[64:65], v[150:151], v[26:27] op_sel:[0,1,0] op_sel_hi:[1,1,1]
	v_pk_fma_f32 v[24:25], v[66:67], v[150:151], v[24:25] op_sel:[0,1,0] op_sel_hi:[1,1,1]
	v_pk_fma_f32 v[22:23], v[68:69], v[150:151], v[22:23] op_sel:[0,1,0] op_sel_hi:[1,1,1]
	v_pk_fma_f32 v[20:21], v[70:71], v[150:151], v[20:21] op_sel:[0,1,0] op_sel_hi:[1,1,1]
	v_pk_fma_f32 v[18:19], v[72:73], v[150:151], v[18:19] op_sel:[0,1,0] op_sel_hi:[1,1,1]
	v_pk_fma_f32 v[16:17], v[74:75], v[150:151], v[16:17] op_sel:[0,1,0] op_sel_hi:[1,1,1]
	ds_read_b128 v[60:63], v32 offset:832
	ds_read_b128 v[64:67], v32 offset:848
	ds_read_b128 v[68:71], v32 offset:864
	ds_read_b128 v[72:75], v32 offset:880
	s_waitcnt lgkmcnt(4)
	v_pk_fma_f32 v[28:29], v[44:45], v[152:153], v[28:29] op_sel_hi:[1,0,1]
	v_pk_fma_f32 v[30:31], v[46:47], v[152:153], v[30:31] op_sel_hi:[1,0,1]
	v_pk_fma_f32 v[26:27], v[48:49], v[152:153], v[26:27] op_sel_hi:[1,0,1]
	v_pk_fma_f32 v[24:25], v[50:51], v[152:153], v[24:25] op_sel_hi:[1,0,1]
	v_pk_fma_f32 v[22:23], v[52:53], v[152:153], v[22:23] op_sel_hi:[1,0,1]
	v_pk_fma_f32 v[20:21], v[54:55], v[152:153], v[20:21] op_sel_hi:[1,0,1]
	v_pk_fma_f32 v[18:19], v[56:57], v[152:153], v[18:19] op_sel_hi:[1,0,1]
	v_pk_fma_f32 v[16:17], v[58:59], v[152:153], v[16:17] op_sel_hi:[1,0,1]
	ds_read_b128 v[44:47], v32 offset:896
	ds_read_b128 v[48:51], v32 offset:912
	ds_read_b128 v[52:55], v32 offset:928
	ds_read_b128 v[56:59], v32 offset:944
	s_waitcnt lgkmcnt(4)
	v_pk_fma_f32 v[28:29], v[60:61], v[152:153], v[28:29] op_sel:[0,1,0] op_sel_hi:[1,1,1]
	v_pk_fma_f32 v[30:31], v[62:63], v[152:153], v[30:31] op_sel:[0,1,0] op_sel_hi:[1,1,1]
	v_pk_fma_f32 v[26:27], v[64:65], v[152:153], v[26:27] op_sel:[0,1,0] op_sel_hi:[1,1,1]
	v_pk_fma_f32 v[24:25], v[66:67], v[152:153], v[24:25] op_sel:[0,1,0] op_sel_hi:[1,1,1]
	v_pk_fma_f32 v[22:23], v[68:69], v[152:153], v[22:23] op_sel:[0,1,0] op_sel_hi:[1,1,1]
	v_pk_fma_f32 v[20:21], v[70:71], v[152:153], v[20:21] op_sel:[0,1,0] op_sel_hi:[1,1,1]
	v_pk_fma_f32 v[18:19], v[72:73], v[152:153], v[18:19] op_sel:[0,1,0] op_sel_hi:[1,1,1]
	v_pk_fma_f32 v[16:17], v[74:75], v[152:153], v[16:17] op_sel:[0,1,0] op_sel_hi:[1,1,1]
	ds_read_b128 v[60:63], v32 offset:960
	ds_read_b128 v[64:67], v32 offset:976
	ds_read_b128 v[68:71], v32 offset:992
	ds_read_b128 v[72:75], v32 offset:1008
	s_waitcnt lgkmcnt(4)
	v_pk_fma_f32 v[28:29], v[44:45], v[154:155], v[28:29] op_sel_hi:[1,0,1]
	v_pk_fma_f32 v[30:31], v[46:47], v[154:155], v[30:31] op_sel_hi:[1,0,1]
	v_pk_fma_f32 v[26:27], v[48:49], v[154:155], v[26:27] op_sel_hi:[1,0,1]
	v_pk_fma_f32 v[24:25], v[50:51], v[154:155], v[24:25] op_sel_hi:[1,0,1]
	v_pk_fma_f32 v[22:23], v[52:53], v[154:155], v[22:23] op_sel_hi:[1,0,1]
	v_pk_fma_f32 v[20:21], v[54:55], v[154:155], v[20:21] op_sel_hi:[1,0,1]
	v_pk_fma_f32 v[18:19], v[56:57], v[154:155], v[18:19] op_sel_hi:[1,0,1]
	v_pk_fma_f32 v[16:17], v[58:59], v[154:155], v[16:17] op_sel_hi:[1,0,1]
	s_waitcnt lgkmcnt(0)
	v_pk_fma_f32 v[28:29], v[60:61], v[154:155], v[28:29] op_sel:[0,1,0] op_sel_hi:[1,1,1]
	v_pk_fma_f32 v[30:31], v[62:63], v[154:155], v[30:31] op_sel:[0,1,0] op_sel_hi:[1,1,1]
	v_pk_fma_f32 v[26:27], v[64:65], v[154:155], v[26:27] op_sel:[0,1,0] op_sel_hi:[1,1,1]
	v_pk_fma_f32 v[24:25], v[66:67], v[154:155], v[24:25] op_sel:[0,1,0] op_sel_hi:[1,1,1]
	v_pk_fma_f32 v[22:23], v[68:69], v[154:155], v[22:23] op_sel:[0,1,0] op_sel_hi:[1,1,1]
	v_pk_fma_f32 v[20:21], v[70:71], v[154:155], v[20:21] op_sel:[0,1,0] op_sel_hi:[1,1,1]
	v_pk_fma_f32 v[18:19], v[72:73], v[154:155], v[18:19] op_sel:[0,1,0] op_sel_hi:[1,1,1]
	v_pk_fma_f32 v[16:17], v[74:75], v[154:155], v[16:17] op_sel:[0,1,0] op_sel_hi:[1,1,1]
	v_add_u32_e32 v32, 0x400, v32
	s_add_i32 s42, s42, -1
	s_cmp_lg_u32 s42, 0
	s_cbranch_scc1 .Lada_loop
	global_load_dword v140, v[76:77], off nt
	v_lshl_add_u64 v[76:77], v[76:77], 0, s[0:1]
	global_load_dword v141, v[76:77], off nt
	v_lshl_add_u64 v[76:77], v[76:77], 0, s[0:1]
	global_load_dword v142, v[76:77], off nt
	v_lshl_add_u64 v[76:77], v[76:77], 0, s[0:1]
	global_load_dword v143, v[76:77], off nt
	v_lshl_add_u64 v[76:77], v[76:77], 0, s[0:1]
	global_load_dword v144, v[76:77], off nt
	v_lshl_add_u64 v[76:77], v[76:77], 0, s[0:1]
	global_load_dword v145, v[76:77], off nt
	v_lshl_add_u64 v[76:77], v[76:77], 0, s[0:1]
	global_load_dword v146, v[76:77], off nt
	v_lshl_add_u64 v[76:77], v[76:77], 0, s[0:1]
	global_load_dword v147, v[76:77], off nt
	v_lshl_add_u64 v[76:77], v[76:77], 0, s[0:1]
	global_load_dword v148, v[76:77], off nt
	v_lshl_add_u64 v[76:77], v[76:77], 0, s[0:1]
	global_load_dword v149, v[76:77], off nt
	v_lshl_add_u64 v[76:77], v[76:77], 0, s[0:1]
	global_load_dword v150, v[76:77], off nt
	v_lshl_add_u64 v[76:77], v[76:77], 0, s[0:1]
	global_load_dword v151, v[76:77], off nt
	v_lshl_add_u64 v[76:77], v[76:77], 0, s[0:1]
	global_load_dword v152, v[76:77], off nt
	v_lshl_add_u64 v[76:77], v[76:77], 0, s[0:1]
	global_load_dword v153, v[76:77], off nt
	v_lshl_add_u64 v[76:77], v[76:77], 0, s[0:1]
	global_load_dword v154, v[76:77], off nt
	v_lshl_add_u64 v[76:77], v[76:77], 0, s[0:1]
	global_load_dword v155, v[76:77], off nt
	v_lshl_add_u64 v[76:77], v[76:77], 0, s[0:1]
	s_waitcnt vmcnt(16)
	ds_read_b128 v[44:47], v32 offset:0
	ds_read_b128 v[48:51], v32 offset:16
	ds_read_b128 v[52:55], v32 offset:32
	ds_read_b128 v[56:59], v32 offset:48
	ds_read_b128 v[60:63], v32 offset:64
	ds_read_b128 v[64:67], v32 offset:80
	ds_read_b128 v[68:71], v32 offset:96
	ds_read_b128 v[72:75], v32 offset:112
	s_waitcnt lgkmcnt(4)
	v_pk_fma_f32 v[28:29], v[44:45], v[104:105], v[28:29] op_sel_hi:[1,0,1]
	v_pk_fma_f32 v[30:31], v[46:47], v[104:105], v[30:31] op_sel_hi:[1,0,1]
	v_pk_fma_f32 v[26:27], v[48:49], v[104:105], v[26:27] op_sel_hi:[1,0,1]
	v_pk_fma_f32 v[24:25], v[50:51], v[104:105], v[24:25] op_sel_hi:[1,0,1]
	v_pk_fma_f32 v[22:23], v[52:53], v[104:105], v[22:23] op_sel_hi:[1,0,1]
	v_pk_fma_f32 v[20:21], v[54:55], v[104:105], v[20:21] op_sel_hi:[1,0,1]
	v_pk_fma_f32 v[18:19], v[56:57], v[104:105], v[18:19] op_sel_hi:[1,0,1]
	v_pk_fma_f32 v[16:17], v[58:59], v[104:105], v[16:17] op_sel_hi:[1,0,1]
	ds_read_b128 v[44:47], v32 offset:128
	ds_read_b128 v[48:51], v32 offset:144
	ds_read_b128 v[52:55], v32 offset:160
	ds_read_b128 v[56:59], v32 offset:176
	s_waitcnt lgkmcnt(4)
	v_pk_fma_f32 v[28:29], v[60:61], v[104:105], v[28:29] op_sel:[0,1,0] op_sel_hi:[1,1,1]
	v_pk_fma_f32 v[30:31], v[62:63], v[104:105], v[30:31] op_sel:[0,1,0] op_sel_hi:[1,1,1]
	v_pk_fma_f32 v[26:27], v[64:65], v[104:105], v[26:27] op_sel:[0,1,0] op_sel_hi:[1,1,1]
	v_pk_fma_f32 v[24:25], v[66:67], v[104:105], v[24:25] op_sel:[0,1,0] op_sel_hi:[1,1,1]
	v_pk_fma_f32 v[22:23], v[68:69], v[104:105], v[22:23] op_sel:[0,1,0] op_sel_hi:[1,1,1]
	v_pk_fma_f32 v[20:21], v[70:71], v[104:105], v[20:21] op_sel:[0,1,0] op_sel_hi:[1,1,1]
	v_pk_fma_f32 v[18:19], v[72:73], v[104:105], v[18:19] op_sel:[0,1,0] op_sel_hi:[1,1,1]
	v_pk_fma_f32 v[16:17], v[74:75], v[104:105], v[16:17] op_sel:[0,1,0] op_sel_hi:[1,1,1]
	ds_read_b128 v[60:63], v32 offset:192
	ds_read_b128 v[64:67], v32 offset:208
	ds_read_b128 v[68:71], v32 offset:224
	ds_read_b128 v[72:75], v32 offset:240
	s_waitcnt lgkmcnt(4)
	v_pk_fma_f32 v[28:29], v[44:45], v[106:107], v[28:29] op_sel_hi:[1,0,1]
	v_pk_fma_f32 v[30:31], v[46:47], v[106:107], v[30:31] op_sel_hi:[1,0,1]
	v_pk_fma_f32 v[26:27], v[48:49], v[106:107], v[26:27] op_sel_hi:[1,0,1]
	v_pk_fma_f32 v[24:25], v[50:51], v[106:107], v[24:25] op_sel_hi:[1,0,1]
	v_pk_fma_f32 v[22:23], v[52:53], v[106:107], v[22:23] op_sel_hi:[1,0,1]
	v_pk_fma_f32 v[20:21], v[54:55], v[106:107], v[20:21] op_sel_hi:[1,0,1]
	v_pk_fma_f32 v[18:19], v[56:57], v[106:107], v[18:19] op_sel_hi:[1,0,1]
	v_pk_fma_f32 v[16:17], v[58:59], v[106:107], v[16:17] op_sel_hi:[1,0,1]
	ds_read_b128 v[44:47], v32 offset:256
	ds_read_b128 v[48:51], v32 offset:272
	ds_read_b128 v[52:55], v32 offset:288
	ds_read_b128 v[56:59], v32 offset:304
	s_waitcnt lgkmcnt(4)
	v_pk_fma_f32 v[28:29], v[60:61], v[106:107], v[28:29] op_sel:[0,1,0] op_sel_hi:[1,1,1]
	v_pk_fma_f32 v[30:31], v[62:63], v[106:107], v[30:31] op_sel:[0,1,0] op_sel_hi:[1,1,1]
	v_pk_fma_f32 v[26:27], v[64:65], v[106:107], v[26:27] op_sel:[0,1,0] op_sel_hi:[1,1,1]
	v_pk_fma_f32 v[24:25], v[66:67], v[106:107], v[24:25] op_sel:[0,1,0] op_sel_hi:[1,1,1]
	v_pk_fma_f32 v[22:23], v[68:69], v[106:107], v[22:23] op_sel:[0,1,0] op_sel_hi:[1,1,1]
	v_pk_fma_f32 v[20:21], v[70:71], v[106:107], v[20:21] op_sel:[0,1,0] op_sel_hi:[1,1,1]
	v_pk_fma_f32 v[18:19], v[72:73], v[106:107], v[18:19] op_sel:[0,1,0] op_sel_hi:[1,1,1]
	v_pk_fma_f32 v[16:17], v[74:75], v[106:107], v[16:17] op_sel:[0,1,0] op_sel_hi:[1,1,1]
	ds_read_b128 v[60:63], v32 offset:320
	ds_read_b128 v[64:67], v32 offset:336
	ds_read_b128 v[68:71], v32 offset:352
	ds_read_b128 v[72:75], v32 offset:368
	s_waitcnt lgkmcnt(4)
	v_pk_fma_f32 v[28:29], v[44:45], v[108:109], v[28:29] op_sel_hi:[1,0,1]
	v_pk_fma_f32 v[30:31], v[46:47], v[108:109], v[30:31] op_sel_hi:[1,0,1]
	v_pk_fma_f32 v[26:27], v[48:49], v[108:109], v[26:27] op_sel_hi:[1,0,1]
	v_pk_fma_f32 v[24:25], v[50:51], v[108:109], v[24:25] op_sel_hi:[1,0,1]
	v_pk_fma_f32 v[22:23], v[52:53], v[108:109], v[22:23] op_sel_hi:[1,0,1]
	v_pk_fma_f32 v[20:21], v[54:55], v[108:109], v[20:21] op_sel_hi:[1,0,1]
	v_pk_fma_f32 v[18:19], v[56:57], v[108:109], v[18:19] op_sel_hi:[1,0,1]
	v_pk_fma_f32 v[16:17], v[58:59], v[108:109], v[16:17] op_sel_hi:[1,0,1]
	ds_read_b128 v[44:47], v32 offset:384
	ds_read_b128 v[48:51], v32 offset:400
	ds_read_b128 v[52:55], v32 offset:416
	ds_read_b128 v[56:59], v32 offset:432
	s_waitcnt lgkmcnt(4)
	v_pk_fma_f32 v[28:29], v[60:61], v[108:109], v[28:29] op_sel:[0,1,0] op_sel_hi:[1,1,1]
	v_pk_fma_f32 v[30:31], v[62:63], v[108:109], v[30:31] op_sel:[0,1,0] op_sel_hi:[1,1,1]
	v_pk_fma_f32 v[26:27], v[64:65], v[108:109], v[26:27] op_sel:[0,1,0] op_sel_hi:[1,1,1]
	v_pk_fma_f32 v[24:25], v[66:67], v[108:109], v[24:25] op_sel:[0,1,0] op_sel_hi:[1,1,1]
	v_pk_fma_f32 v[22:23], v[68:69], v[108:109], v[22:23] op_sel:[0,1,0] op_sel_hi:[1,1,1]
	v_pk_fma_f32 v[20:21], v[70:71], v[108:109], v[20:21] op_sel:[0,1,0] op_sel_hi:[1,1,1]
	v_pk_fma_f32 v[18:19], v[72:73], v[108:109], v[18:19] op_sel:[0,1,0] op_sel_hi:[1,1,1]
	v_pk_fma_f32 v[16:17], v[74:75], v[108:109], v[16:17] op_sel:[0,1,0] op_sel_hi:[1,1,1]
	ds_read_b128 v[60:63], v32 offset:448
	ds_read_b128 v[64:67], v32 offset:464
	ds_read_b128 v[68:71], v32 offset:480
	ds_read_b128 v[72:75], v32 offset:496
	s_waitcnt lgkmcnt(4)
	v_pk_fma_f32 v[28:29], v[44:45], v[110:111], v[28:29] op_sel_hi:[1,0,1]
	v_pk_fma_f32 v[30:31], v[46:47], v[110:111], v[30:31] op_sel_hi:[1,0,1]
	v_pk_fma_f32 v[26:27], v[48:49], v[110:111], v[26:27] op_sel_hi:[1,0,1]
	v_pk_fma_f32 v[24:25], v[50:51], v[110:111], v[24:25] op_sel_hi:[1,0,1]
	v_pk_fma_f32 v[22:23], v[52:53], v[110:111], v[22:23] op_sel_hi:[1,0,1]
	v_pk_fma_f32 v[20:21], v[54:55], v[110:111], v[20:21] op_sel_hi:[1,0,1]
	v_pk_fma_f32 v[18:19], v[56:57], v[110:111], v[18:19] op_sel_hi:[1,0,1]
	v_pk_fma_f32 v[16:17], v[58:59], v[110:111], v[16:17] op_sel_hi:[1,0,1]
	ds_read_b128 v[44:47], v32 offset:512
	ds_read_b128 v[48:51], v32 offset:528
	ds_read_b128 v[52:55], v32 offset:544
	ds_read_b128 v[56:59], v32 offset:560
	s_waitcnt lgkmcnt(4)
	v_pk_fma_f32 v[28:29], v[60:61], v[110:111], v[28:29] op_sel:[0,1,0] op_sel_hi:[1,1,1]
	v_pk_fma_f32 v[30:31], v[62:63], v[110:111], v[30:31] op_sel:[0,1,0] op_sel_hi:[1,1,1]
	v_pk_fma_f32 v[26:27], v[64:65], v[110:111], v[26:27] op_sel:[0,1,0] op_sel_hi:[1,1,1]
	v_pk_fma_f32 v[24:25], v[66:67], v[110:111], v[24:25] op_sel:[0,1,0] op_sel_hi:[1,1,1]
	v_pk_fma_f32 v[22:23], v[68:69], v[110:111], v[22:23] op_sel:[0,1,0] op_sel_hi:[1,1,1]
	v_pk_fma_f32 v[20:21], v[70:71], v[110:111], v[20:21] op_sel:[0,1,0] op_sel_hi:[1,1,1]
	v_pk_fma_f32 v[18:19], v[72:73], v[110:111], v[18:19] op_sel:[0,1,0] op_sel_hi:[1,1,1]
	v_pk_fma_f32 v[16:17], v[74:75], v[110:111], v[16:17] op_sel:[0,1,0] op_sel_hi:[1,1,1]
	ds_read_b128 v[60:63], v32 offset:576
	ds_read_b128 v[64:67], v32 offset:592
	ds_read_b128 v[68:71], v32 offset:608
	ds_read_b128 v[72:75], v32 offset:624
	s_waitcnt lgkmcnt(4)
	v_pk_fma_f32 v[28:29], v[44:45], v[112:113], v[28:29] op_sel_hi:[1,0,1]
	v_pk_fma_f32 v[30:31], v[46:47], v[112:113], v[30:31] op_sel_hi:[1,0,1]
	v_pk_fma_f32 v[26:27], v[48:49], v[112:113], v[26:27] op_sel_hi:[1,0,1]
	v_pk_fma_f32 v[24:25], v[50:51], v[112:113], v[24:25] op_sel_hi:[1,0,1]
	v_pk_fma_f32 v[22:23], v[52:53], v[112:113], v[22:23] op_sel_hi:[1,0,1]
	v_pk_fma_f32 v[20:21], v[54:55], v[112:113], v[20:21] op_sel_hi:[1,0,1]
	v_pk_fma_f32 v[18:19], v[56:57], v[112:113], v[18:19] op_sel_hi:[1,0,1]
	v_pk_fma_f32 v[16:17], v[58:59], v[112:113], v[16:17] op_sel_hi:[1,0,1]
	ds_read_b128 v[44:47], v32 offset:640
	ds_read_b128 v[48:51], v32 offset:656
	ds_read_b128 v[52:55], v32 offset:672
	ds_read_b128 v[56:59], v32 offset:688
	s_waitcnt lgkmcnt(4)
	v_pk_fma_f32 v[28:29], v[60:61], v[112:113], v[28:29] op_sel:[0,1,0] op_sel_hi:[1,1,1]
	v_pk_fma_f32 v[30:31], v[62:63], v[112:113], v[30:31] op_sel:[0,1,0] op_sel_hi:[1,1,1]
	v_pk_fma_f32 v[26:27], v[64:65], v[112:113], v[26:27] op_sel:[0,1,0] op_sel_hi:[1,1,1]
	v_pk_fma_f32 v[24:25], v[66:67], v[112:113], v[24:25] op_sel:[0,1,0] op_sel_hi:[1,1,1]
	v_pk_fma_f32 v[22:23], v[68:69], v[112:113], v[22:23] op_sel:[0,1,0] op_sel_hi:[1,1,1]
	v_pk_fma_f32 v[20:21], v[70:71], v[112:113], v[20:21] op_sel:[0,1,0] op_sel_hi:[1,1,1]
	v_pk_fma_f32 v[18:19], v[72:73], v[112:113], v[18:19] op_sel:[0,1,0] op_sel_hi:[1,1,1]
	v_pk_fma_f32 v[16:17], v[74:75], v[112:113], v[16:17] op_sel:[0,1,0] op_sel_hi:[1,1,1]
	ds_read_b128 v[60:63], v32 offset:704
	ds_read_b128 v[64:67], v32 offset:720
	ds_read_b128 v[68:71], v32 offset:736
	ds_read_b128 v[72:75], v32 offset:752
	s_waitcnt lgkmcnt(4)
	v_pk_fma_f32 v[28:29], v[44:45], v[114:115], v[28:29] op_sel_hi:[1,0,1]
	v_pk_fma_f32 v[30:31], v[46:47], v[114:115], v[30:31] op_sel_hi:[1,0,1]
	v_pk_fma_f32 v[26:27], v[48:49], v[114:115], v[26:27] op_sel_hi:[1,0,1]
	v_pk_fma_f32 v[24:25], v[50:51], v[114:115], v[24:25] op_sel_hi:[1,0,1]
	v_pk_fma_f32 v[22:23], v[52:53], v[114:115], v[22:23] op_sel_hi:[1,0,1]
	v_pk_fma_f32 v[20:21], v[54:55], v[114:115], v[20:21] op_sel_hi:[1,0,1]
	v_pk_fma_f32 v[18:19], v[56:57], v[114:115], v[18:19] op_sel_hi:[1,0,1]
	v_pk_fma_f32 v[16:17], v[58:59], v[114:115], v[16:17] op_sel_hi:[1,0,1]
	ds_read_b128 v[44:47], v32 offset:768
	ds_read_b128 v[48:51], v32 offset:784
	ds_read_b128 v[52:55], v32 offset:800
	ds_read_b128 v[56:59], v32 offset:816
	s_waitcnt lgkmcnt(4)
	v_pk_fma_f32 v[28:29], v[60:61], v[114:115], v[28:29] op_sel:[0,1,0] op_sel_hi:[1,1,1]
	v_pk_fma_f32 v[30:31], v[62:63], v[114:115], v[30:31] op_sel:[0,1,0] op_sel_hi:[1,1,1]
	v_pk_fma_f32 v[26:27], v[64:65], v[114:115], v[26:27] op_sel:[0,1,0] op_sel_hi:[1,1,1]
	v_pk_fma_f32 v[24:25], v[66:67], v[114:115], v[24:25] op_sel:[0,1,0] op_sel_hi:[1,1,1]
	v_pk_fma_f32 v[22:23], v[68:69], v[114:115], v[22:23] op_sel:[0,1,0] op_sel_hi:[1,1,1]
	v_pk_fma_f32 v[20:21], v[70:71], v[114:115], v[20:21] op_sel:[0,1,0] op_sel_hi:[1,1,1]
	v_pk_fma_f32 v[18:19], v[72:73], v[114:115], v[18:19] op_sel:[0,1,0] op_sel_hi:[1,1,1]
	v_pk_fma_f32 v[16:17], v[74:75], v[114:115], v[16:17] op_sel:[0,1,0] op_sel_hi:[1,1,1]
	ds_read_b128 v[60:63], v32 offset:832
	ds_read_b128 v[64:67], v32 offset:848
	ds_read_b128 v[68:71], v32 offset:864
	ds_read_b128 v[72:75], v32 offset:880
	s_waitcnt lgkmcnt(4)
	v_pk_fma_f32 v[28:29], v[44:45], v[116:117], v[28:29] op_sel_hi:[1,0,1]
	v_pk_fma_f32 v[30:31], v[46:47], v[116:117], v[30:31] op_sel_hi:[1,0,1]
	v_pk_fma_f32 v[26:27], v[48:49], v[116:117], v[26:27] op_sel_hi:[1,0,1]
	v_pk_fma_f32 v[24:25], v[50:51], v[116:117], v[24:25] op_sel_hi:[1,0,1]
	v_pk_fma_f32 v[22:23], v[52:53], v[116:117], v[22:23] op_sel_hi:[1,0,1]
	v_pk_fma_f32 v[20:21], v[54:55], v[116:117], v[20:21] op_sel_hi:[1,0,1]
	v_pk_fma_f32 v[18:19], v[56:57], v[116:117], v[18:19] op_sel_hi:[1,0,1]
	v_pk_fma_f32 v[16:17], v[58:59], v[116:117], v[16:17] op_sel_hi:[1,0,1]
	ds_read_b128 v[44:47], v32 offset:896
	ds_read_b128 v[48:51], v32 offset:912
	ds_read_b128 v[52:55], v32 offset:928
	ds_read_b128 v[56:59], v32 offset:944
	s_waitcnt lgkmcnt(4)
	v_pk_fma_f32 v[28:29], v[60:61], v[116:117], v[28:29] op_sel:[0,1,0] op_sel_hi:[1,1,1]
	v_pk_fma_f32 v[30:31], v[62:63], v[116:117], v[30:31] op_sel:[0,1,0] op_sel_hi:[1,1,1]
	v_pk_fma_f32 v[26:27], v[64:65], v[116:117], v[26:27] op_sel:[0,1,0] op_sel_hi:[1,1,1]
	v_pk_fma_f32 v[24:25], v[66:67], v[116:117], v[24:25] op_sel:[0,1,0] op_sel_hi:[1,1,1]
	v_pk_fma_f32 v[22:23], v[68:69], v[116:117], v[22:23] op_sel:[0,1,0] op_sel_hi:[1,1,1]
	v_pk_fma_f32 v[20:21], v[70:71], v[116:117], v[20:21] op_sel:[0,1,0] op_sel_hi:[1,1,1]
	v_pk_fma_f32 v[18:19], v[72:73], v[116:117], v[18:19] op_sel:[0,1,0] op_sel_hi:[1,1,1]
	v_pk_fma_f32 v[16:17], v[74:75], v[116:117], v[16:17] op_sel:[0,1,0] op_sel_hi:[1,1,1]
	ds_read_b128 v[60:63], v32 offset:960
	ds_read_b128 v[64:67], v32 offset:976
	ds_read_b128 v[68:71], v32 offset:992
	ds_read_b128 v[72:75], v32 offset:1008
	s_waitcnt lgkmcnt(4)
	v_pk_fma_f32 v[28:29], v[44:45], v[118:119], v[28:29] op_sel_hi:[1,0,1]
	v_pk_fma_f32 v[30:31], v[46:47], v[118:119], v[30:31] op_sel_hi:[1,0,1]
	v_pk_fma_f32 v[26:27], v[48:49], v[118:119], v[26:27] op_sel_hi:[1,0,1]
	v_pk_fma_f32 v[24:25], v[50:51], v[118:119], v[24:25] op_sel_hi:[1,0,1]
	v_pk_fma_f32 v[22:23], v[52:53], v[118:119], v[22:23] op_sel_hi:[1,0,1]
	v_pk_fma_f32 v[20:21], v[54:55], v[118:119], v[20:21] op_sel_hi:[1,0,1]
	v_pk_fma_f32 v[18:19], v[56:57], v[118:119], v[18:19] op_sel_hi:[1,0,1]
	v_pk_fma_f32 v[16:17], v[58:59], v[118:119], v[16:17] op_sel_hi:[1,0,1]
	s_waitcnt lgkmcnt(0)
	v_pk_fma_f32 v[28:29], v[60:61], v[118:119], v[28:29] op_sel:[0,1,0] op_sel_hi:[1,1,1]
	v_pk_fma_f32 v[30:31], v[62:63], v[118:119], v[30:31] op_sel:[0,1,0] op_sel_hi:[1,1,1]
	v_pk_fma_f32 v[26:27], v[64:65], v[118:119], v[26:27] op_sel:[0,1,0] op_sel_hi:[1,1,1]
	v_pk_fma_f32 v[24:25], v[66:67], v[118:119], v[24:25] op_sel:[0,1,0] op_sel_hi:[1,1,1]
	v_pk_fma_f32 v[22:23], v[68:69], v[118:119], v[22:23] op_sel:[0,1,0] op_sel_hi:[1,1,1]
	v_pk_fma_f32 v[20:21], v[70:71], v[118:119], v[20:21] op_sel:[0,1,0] op_sel_hi:[1,1,1]
	v_pk_fma_f32 v[18:19], v[72:73], v[118:119], v[18:19] op_sel:[0,1,0] op_sel_hi:[1,1,1]
	v_pk_fma_f32 v[16:17], v[74:75], v[118:119], v[16:17] op_sel:[0,1,0] op_sel_hi:[1,1,1]
	v_add_u32_e32 v32, 0x400, v32
	s_waitcnt vmcnt(0)
	ds_read_b128 v[44:47], v32 offset:0
	ds_read_b128 v[48:51], v32 offset:16
	ds_read_b128 v[52:55], v32 offset:32
	ds_read_b128 v[56:59], v32 offset:48
	ds_read_b128 v[60:63], v32 offset:64
	ds_read_b128 v[64:67], v32 offset:80
	ds_read_b128 v[68:71], v32 offset:96
	ds_read_b128 v[72:75], v32 offset:112
	s_waitcnt lgkmcnt(4)
	v_pk_fma_f32 v[28:29], v[44:45], v[140:141], v[28:29] op_sel_hi:[1,0,1]
	v_pk_fma_f32 v[30:31], v[46:47], v[140:141], v[30:31] op_sel_hi:[1,0,1]
	v_pk_fma_f32 v[26:27], v[48:49], v[140:141], v[26:27] op_sel_hi:[1,0,1]
	v_pk_fma_f32 v[24:25], v[50:51], v[140:141], v[24:25] op_sel_hi:[1,0,1]
	v_pk_fma_f32 v[22:23], v[52:53], v[140:141], v[22:23] op_sel_hi:[1,0,1]
	v_pk_fma_f32 v[20:21], v[54:55], v[140:141], v[20:21] op_sel_hi:[1,0,1]
	v_pk_fma_f32 v[18:19], v[56:57], v[140:141], v[18:19] op_sel_hi:[1,0,1]
	v_pk_fma_f32 v[16:17], v[58:59], v[140:141], v[16:17] op_sel_hi:[1,0,1]
	ds_read_b128 v[44:47], v32 offset:128
	ds_read_b128 v[48:51], v32 offset:144
	ds_read_b128 v[52:55], v32 offset:160
	ds_read_b128 v[56:59], v32 offset:176
	s_waitcnt lgkmcnt(4)
	v_pk_fma_f32 v[28:29], v[60:61], v[140:141], v[28:29] op_sel:[0,1,0] op_sel_hi:[1,1,1]
	v_pk_fma_f32 v[30:31], v[62:63], v[140:141], v[30:31] op_sel:[0,1,0] op_sel_hi:[1,1,1]
	v_pk_fma_f32 v[26:27], v[64:65], v[140:141], v[26:27] op_sel:[0,1,0] op_sel_hi:[1,1,1]
	v_pk_fma_f32 v[24:25], v[66:67], v[140:141], v[24:25] op_sel:[0,1,0] op_sel_hi:[1,1,1]
	v_pk_fma_f32 v[22:23], v[68:69], v[140:141], v[22:23] op_sel:[0,1,0] op_sel_hi:[1,1,1]
	v_pk_fma_f32 v[20:21], v[70:71], v[140:141], v[20:21] op_sel:[0,1,0] op_sel_hi:[1,1,1]
	v_pk_fma_f32 v[18:19], v[72:73], v[140:141], v[18:19] op_sel:[0,1,0] op_sel_hi:[1,1,1]
	v_pk_fma_f32 v[16:17], v[74:75], v[140:141], v[16:17] op_sel:[0,1,0] op_sel_hi:[1,1,1]
	ds_read_b128 v[60:63], v32 offset:192
	ds_read_b128 v[64:67], v32 offset:208
	ds_read_b128 v[68:71], v32 offset:224
	ds_read_b128 v[72:75], v32 offset:240
	s_waitcnt lgkmcnt(4)
	v_pk_fma_f32 v[28:29], v[44:45], v[142:143], v[28:29] op_sel_hi:[1,0,1]
	v_pk_fma_f32 v[30:31], v[46:47], v[142:143], v[30:31] op_sel_hi:[1,0,1]
	v_pk_fma_f32 v[26:27], v[48:49], v[142:143], v[26:27] op_sel_hi:[1,0,1]
	v_pk_fma_f32 v[24:25], v[50:51], v[142:143], v[24:25] op_sel_hi:[1,0,1]
	v_pk_fma_f32 v[22:23], v[52:53], v[142:143], v[22:23] op_sel_hi:[1,0,1]
	v_pk_fma_f32 v[20:21], v[54:55], v[142:143], v[20:21] op_sel_hi:[1,0,1]
	v_pk_fma_f32 v[18:19], v[56:57], v[142:143], v[18:19] op_sel_hi:[1,0,1]
	v_pk_fma_f32 v[16:17], v[58:59], v[142:143], v[16:17] op_sel_hi:[1,0,1]
	ds_read_b128 v[44:47], v32 offset:256
	ds_read_b128 v[48:51], v32 offset:272
	ds_read_b128 v[52:55], v32 offset:288
	ds_read_b128 v[56:59], v32 offset:304
	s_waitcnt lgkmcnt(4)
	v_pk_fma_f32 v[28:29], v[60:61], v[142:143], v[28:29] op_sel:[0,1,0] op_sel_hi:[1,1,1]
	v_pk_fma_f32 v[30:31], v[62:63], v[142:143], v[30:31] op_sel:[0,1,0] op_sel_hi:[1,1,1]
	v_pk_fma_f32 v[26:27], v[64:65], v[142:143], v[26:27] op_sel:[0,1,0] op_sel_hi:[1,1,1]
	v_pk_fma_f32 v[24:25], v[66:67], v[142:143], v[24:25] op_sel:[0,1,0] op_sel_hi:[1,1,1]
	v_pk_fma_f32 v[22:23], v[68:69], v[142:143], v[22:23] op_sel:[0,1,0] op_sel_hi:[1,1,1]
	v_pk_fma_f32 v[20:21], v[70:71], v[142:143], v[20:21] op_sel:[0,1,0] op_sel_hi:[1,1,1]
	v_pk_fma_f32 v[18:19], v[72:73], v[142:143], v[18:19] op_sel:[0,1,0] op_sel_hi:[1,1,1]
	v_pk_fma_f32 v[16:17], v[74:75], v[142:143], v[16:17] op_sel:[0,1,0] op_sel_hi:[1,1,1]
	ds_read_b128 v[60:63], v32 offset:320
	ds_read_b128 v[64:67], v32 offset:336
	ds_read_b128 v[68:71], v32 offset:352
	ds_read_b128 v[72:75], v32 offset:368
	s_waitcnt lgkmcnt(4)
	v_pk_fma_f32 v[28:29], v[44:45], v[144:145], v[28:29] op_sel_hi:[1,0,1]
	v_pk_fma_f32 v[30:31], v[46:47], v[144:145], v[30:31] op_sel_hi:[1,0,1]
	v_pk_fma_f32 v[26:27], v[48:49], v[144:145], v[26:27] op_sel_hi:[1,0,1]
	v_pk_fma_f32 v[24:25], v[50:51], v[144:145], v[24:25] op_sel_hi:[1,0,1]
	v_pk_fma_f32 v[22:23], v[52:53], v[144:145], v[22:23] op_sel_hi:[1,0,1]
	v_pk_fma_f32 v[20:21], v[54:55], v[144:145], v[20:21] op_sel_hi:[1,0,1]
	v_pk_fma_f32 v[18:19], v[56:57], v[144:145], v[18:19] op_sel_hi:[1,0,1]
	v_pk_fma_f32 v[16:17], v[58:59], v[144:145], v[16:17] op_sel_hi:[1,0,1]
	ds_read_b128 v[44:47], v32 offset:384
	ds_read_b128 v[48:51], v32 offset:400
	ds_read_b128 v[52:55], v32 offset:416
	ds_read_b128 v[56:59], v32 offset:432
	s_waitcnt lgkmcnt(4)
	v_pk_fma_f32 v[28:29], v[60:61], v[144:145], v[28:29] op_sel:[0,1,0] op_sel_hi:[1,1,1]
	v_pk_fma_f32 v[30:31], v[62:63], v[144:145], v[30:31] op_sel:[0,1,0] op_sel_hi:[1,1,1]
	v_pk_fma_f32 v[26:27], v[64:65], v[144:145], v[26:27] op_sel:[0,1,0] op_sel_hi:[1,1,1]
	v_pk_fma_f32 v[24:25], v[66:67], v[144:145], v[24:25] op_sel:[0,1,0] op_sel_hi:[1,1,1]
	v_pk_fma_f32 v[22:23], v[68:69], v[144:145], v[22:23] op_sel:[0,1,0] op_sel_hi:[1,1,1]
	v_pk_fma_f32 v[20:21], v[70:71], v[144:145], v[20:21] op_sel:[0,1,0] op_sel_hi:[1,1,1]
	v_pk_fma_f32 v[18:19], v[72:73], v[144:145], v[18:19] op_sel:[0,1,0] op_sel_hi:[1,1,1]
	v_pk_fma_f32 v[16:17], v[74:75], v[144:145], v[16:17] op_sel:[0,1,0] op_sel_hi:[1,1,1]
	ds_read_b128 v[60:63], v32 offset:448
	ds_read_b128 v[64:67], v32 offset:464
	ds_read_b128 v[68:71], v32 offset:480
	ds_read_b128 v[72:75], v32 offset:496
	s_waitcnt lgkmcnt(4)
	v_pk_fma_f32 v[28:29], v[44:45], v[146:147], v[28:29] op_sel_hi:[1,0,1]
	v_pk_fma_f32 v[30:31], v[46:47], v[146:147], v[30:31] op_sel_hi:[1,0,1]
	v_pk_fma_f32 v[26:27], v[48:49], v[146:147], v[26:27] op_sel_hi:[1,0,1]
	v_pk_fma_f32 v[24:25], v[50:51], v[146:147], v[24:25] op_sel_hi:[1,0,1]
	v_pk_fma_f32 v[22:23], v[52:53], v[146:147], v[22:23] op_sel_hi:[1,0,1]
	v_pk_fma_f32 v[20:21], v[54:55], v[146:147], v[20:21] op_sel_hi:[1,0,1]
	v_pk_fma_f32 v[18:19], v[56:57], v[146:147], v[18:19] op_sel_hi:[1,0,1]
	v_pk_fma_f32 v[16:17], v[58:59], v[146:147], v[16:17] op_sel_hi:[1,0,1]
	ds_read_b128 v[44:47], v32 offset:512
	ds_read_b128 v[48:51], v32 offset:528
	ds_read_b128 v[52:55], v32 offset:544
	ds_read_b128 v[56:59], v32 offset:560
	s_waitcnt lgkmcnt(4)
	v_pk_fma_f32 v[28:29], v[60:61], v[146:147], v[28:29] op_sel:[0,1,0] op_sel_hi:[1,1,1]
	v_pk_fma_f32 v[30:31], v[62:63], v[146:147], v[30:31] op_sel:[0,1,0] op_sel_hi:[1,1,1]
	v_pk_fma_f32 v[26:27], v[64:65], v[146:147], v[26:27] op_sel:[0,1,0] op_sel_hi:[1,1,1]
	v_pk_fma_f32 v[24:25], v[66:67], v[146:147], v[24:25] op_sel:[0,1,0] op_sel_hi:[1,1,1]
	v_pk_fma_f32 v[22:23], v[68:69], v[146:147], v[22:23] op_sel:[0,1,0] op_sel_hi:[1,1,1]
	v_pk_fma_f32 v[20:21], v[70:71], v[146:147], v[20:21] op_sel:[0,1,0] op_sel_hi:[1,1,1]
	v_pk_fma_f32 v[18:19], v[72:73], v[146:147], v[18:19] op_sel:[0,1,0] op_sel_hi:[1,1,1]
	v_pk_fma_f32 v[16:17], v[74:75], v[146:147], v[16:17] op_sel:[0,1,0] op_sel_hi:[1,1,1]
	ds_read_b128 v[60:63], v32 offset:576
	ds_read_b128 v[64:67], v32 offset:592
	ds_read_b128 v[68:71], v32 offset:608
	ds_read_b128 v[72:75], v32 offset:624
	s_waitcnt lgkmcnt(4)
	v_pk_fma_f32 v[28:29], v[44:45], v[148:149], v[28:29] op_sel_hi:[1,0,1]
	v_pk_fma_f32 v[30:31], v[46:47], v[148:149], v[30:31] op_sel_hi:[1,0,1]
	v_pk_fma_f32 v[26:27], v[48:49], v[148:149], v[26:27] op_sel_hi:[1,0,1]
	v_pk_fma_f32 v[24:25], v[50:51], v[148:149], v[24:25] op_sel_hi:[1,0,1]
	v_pk_fma_f32 v[22:23], v[52:53], v[148:149], v[22:23] op_sel_hi:[1,0,1]
	v_pk_fma_f32 v[20:21], v[54:55], v[148:149], v[20:21] op_sel_hi:[1,0,1]
	v_pk_fma_f32 v[18:19], v[56:57], v[148:149], v[18:19] op_sel_hi:[1,0,1]
	v_pk_fma_f32 v[16:17], v[58:59], v[148:149], v[16:17] op_sel_hi:[1,0,1]
	ds_read_b128 v[44:47], v32 offset:640
	ds_read_b128 v[48:51], v32 offset:656
	ds_read_b128 v[52:55], v32 offset:672
	ds_read_b128 v[56:59], v32 offset:688
	s_waitcnt lgkmcnt(4)
	v_pk_fma_f32 v[28:29], v[60:61], v[148:149], v[28:29] op_sel:[0,1,0] op_sel_hi:[1,1,1]
	v_pk_fma_f32 v[30:31], v[62:63], v[148:149], v[30:31] op_sel:[0,1,0] op_sel_hi:[1,1,1]
	v_pk_fma_f32 v[26:27], v[64:65], v[148:149], v[26:27] op_sel:[0,1,0] op_sel_hi:[1,1,1]
	v_pk_fma_f32 v[24:25], v[66:67], v[148:149], v[24:25] op_sel:[0,1,0] op_sel_hi:[1,1,1]
	v_pk_fma_f32 v[22:23], v[68:69], v[148:149], v[22:23] op_sel:[0,1,0] op_sel_hi:[1,1,1]
	v_pk_fma_f32 v[20:21], v[70:71], v[148:149], v[20:21] op_sel:[0,1,0] op_sel_hi:[1,1,1]
	v_pk_fma_f32 v[18:19], v[72:73], v[148:149], v[18:19] op_sel:[0,1,0] op_sel_hi:[1,1,1]
	v_pk_fma_f32 v[16:17], v[74:75], v[148:149], v[16:17] op_sel:[0,1,0] op_sel_hi:[1,1,1]
	ds_read_b128 v[60:63], v32 offset:704
	ds_read_b128 v[64:67], v32 offset:720
	ds_read_b128 v[68:71], v32 offset:736
	ds_read_b128 v[72:75], v32 offset:752
	s_waitcnt lgkmcnt(4)
	v_pk_fma_f32 v[28:29], v[44:45], v[150:151], v[28:29] op_sel_hi:[1,0,1]
	v_pk_fma_f32 v[30:31], v[46:47], v[150:151], v[30:31] op_sel_hi:[1,0,1]
	v_pk_fma_f32 v[26:27], v[48:49], v[150:151], v[26:27] op_sel_hi:[1,0,1]
	v_pk_fma_f32 v[24:25], v[50:51], v[150:151], v[24:25] op_sel_hi:[1,0,1]
	v_pk_fma_f32 v[22:23], v[52:53], v[150:151], v[22:23] op_sel_hi:[1,0,1]
	v_pk_fma_f32 v[20:21], v[54:55], v[150:151], v[20:21] op_sel_hi:[1,0,1]
	v_pk_fma_f32 v[18:19], v[56:57], v[150:151], v[18:19] op_sel_hi:[1,0,1]
	v_pk_fma_f32 v[16:17], v[58:59], v[150:151], v[16:17] op_sel_hi:[1,0,1]
	ds_read_b128 v[44:47], v32 offset:768
	ds_read_b128 v[48:51], v32 offset:784
	ds_read_b128 v[52:55], v32 offset:800
	ds_read_b128 v[56:59], v32 offset:816
	s_waitcnt lgkmcnt(4)
	v_pk_fma_f32 v[28:29], v[60:61], v[150:151], v[28:29] op_sel:[0,1,0] op_sel_hi:[1,1,1]
	v_pk_fma_f32 v[30:31], v[62:63], v[150:151], v[30:31] op_sel:[0,1,0] op_sel_hi:[1,1,1]
	v_pk_fma_f32 v[26:27], v[64:65], v[150:151], v[26:27] op_sel:[0,1,0] op_sel_hi:[1,1,1]
	v_pk_fma_f32 v[24:25], v[66:67], v[150:151], v[24:25] op_sel:[0,1,0] op_sel_hi:[1,1,1]
	v_pk_fma_f32 v[22:23], v[68:69], v[150:151], v[22:23] op_sel:[0,1,0] op_sel_hi:[1,1,1]
	v_pk_fma_f32 v[20:21], v[70:71], v[150:151], v[20:21] op_sel:[0,1,0] op_sel_hi:[1,1,1]
	v_pk_fma_f32 v[18:19], v[72:73], v[150:151], v[18:19] op_sel:[0,1,0] op_sel_hi:[1,1,1]
	v_pk_fma_f32 v[16:17], v[74:75], v[150:151], v[16:17] op_sel:[0,1,0] op_sel_hi:[1,1,1]
	ds_read_b128 v[60:63], v32 offset:832
	ds_read_b128 v[64:67], v32 offset:848
	ds_read_b128 v[68:71], v32 offset:864
	ds_read_b128 v[72:75], v32 offset:880
	s_waitcnt lgkmcnt(4)
	v_pk_fma_f32 v[28:29], v[44:45], v[152:153], v[28:29] op_sel_hi:[1,0,1]
	v_pk_fma_f32 v[30:31], v[46:47], v[152:153], v[30:31] op_sel_hi:[1,0,1]
	v_pk_fma_f32 v[26:27], v[48:49], v[152:153], v[26:27] op_sel_hi:[1,0,1]
	v_pk_fma_f32 v[24:25], v[50:51], v[152:153], v[24:25] op_sel_hi:[1,0,1]
	v_pk_fma_f32 v[22:23], v[52:53], v[152:153], v[22:23] op_sel_hi:[1,0,1]
	v_pk_fma_f32 v[20:21], v[54:55], v[152:153], v[20:21] op_sel_hi:[1,0,1]
	v_pk_fma_f32 v[18:19], v[56:57], v[152:153], v[18:19] op_sel_hi:[1,0,1]
	v_pk_fma_f32 v[16:17], v[58:59], v[152:153], v[16:17] op_sel_hi:[1,0,1]
	ds_read_b128 v[44:47], v32 offset:896
	ds_read_b128 v[48:51], v32 offset:912
	ds_read_b128 v[52:55], v32 offset:928
	ds_read_b128 v[56:59], v32 offset:944
	s_waitcnt lgkmcnt(4)
	v_pk_fma_f32 v[28:29], v[60:61], v[152:153], v[28:29] op_sel:[0,1,0] op_sel_hi:[1,1,1]
	v_pk_fma_f32 v[30:31], v[62:63], v[152:153], v[30:31] op_sel:[0,1,0] op_sel_hi:[1,1,1]
	v_pk_fma_f32 v[26:27], v[64:65], v[152:153], v[26:27] op_sel:[0,1,0] op_sel_hi:[1,1,1]
	v_pk_fma_f32 v[24:25], v[66:67], v[152:153], v[24:25] op_sel:[0,1,0] op_sel_hi:[1,1,1]
	v_pk_fma_f32 v[22:23], v[68:69], v[152:153], v[22:23] op_sel:[0,1,0] op_sel_hi:[1,1,1]
	v_pk_fma_f32 v[20:21], v[70:71], v[152:153], v[20:21] op_sel:[0,1,0] op_sel_hi:[1,1,1]
	v_pk_fma_f32 v[18:19], v[72:73], v[152:153], v[18:19] op_sel:[0,1,0] op_sel_hi:[1,1,1]
	v_pk_fma_f32 v[16:17], v[74:75], v[152:153], v[16:17] op_sel:[0,1,0] op_sel_hi:[1,1,1]
	ds_read_b128 v[60:63], v32 offset:960
	ds_read_b128 v[64:67], v32 offset:976
	ds_read_b128 v[68:71], v32 offset:992
	ds_read_b128 v[72:75], v32 offset:1008
	s_waitcnt lgkmcnt(4)
	v_pk_fma_f32 v[28:29], v[44:45], v[154:155], v[28:29] op_sel_hi:[1,0,1]
	v_pk_fma_f32 v[30:31], v[46:47], v[154:155], v[30:31] op_sel_hi:[1,0,1]
	v_pk_fma_f32 v[26:27], v[48:49], v[154:155], v[26:27] op_sel_hi:[1,0,1]
	v_pk_fma_f32 v[24:25], v[50:51], v[154:155], v[24:25] op_sel_hi:[1,0,1]
	v_pk_fma_f32 v[22:23], v[52:53], v[154:155], v[22:23] op_sel_hi:[1,0,1]
	v_pk_fma_f32 v[20:21], v[54:55], v[154:155], v[20:21] op_sel_hi:[1,0,1]
	v_pk_fma_f32 v[18:19], v[56:57], v[154:155], v[18:19] op_sel_hi:[1,0,1]
	v_pk_fma_f32 v[16:17], v[58:59], v[154:155], v[16:17] op_sel_hi:[1,0,1]
	s_waitcnt lgkmcnt(0)
	v_pk_fma_f32 v[28:29], v[60:61], v[154:155], v[28:29] op_sel:[0,1,0] op_sel_hi:[1,1,1]
	v_pk_fma_f32 v[30:31], v[62:63], v[154:155], v[30:31] op_sel:[0,1,0] op_sel_hi:[1,1,1]
	v_pk_fma_f32 v[26:27], v[64:65], v[154:155], v[26:27] op_sel:[0,1,0] op_sel_hi:[1,1,1]
	v_pk_fma_f32 v[24:25], v[66:67], v[154:155], v[24:25] op_sel:[0,1,0] op_sel_hi:[1,1,1]
	v_pk_fma_f32 v[22:23], v[68:69], v[154:155], v[22:23] op_sel:[0,1,0] op_sel_hi:[1,1,1]
	v_pk_fma_f32 v[20:21], v[70:71], v[154:155], v[20:21] op_sel:[0,1,0] op_sel_hi:[1,1,1]
	v_pk_fma_f32 v[18:19], v[72:73], v[154:155], v[18:19] op_sel:[0,1,0] op_sel_hi:[1,1,1]
	v_pk_fma_f32 v[16:17], v[74:75], v[154:155], v[16:17] op_sel:[0,1,0] op_sel_hi:[1,1,1]
	v_add_u32_e32 v32, 0x400, v32
	s_mul_i32 s0, s6, 0x2400
	s_add_i32 s0, s0, s40
	v_or_b32_e32 v14, s0, v0
	v_readlane_b32 s44, v254, 24
	v_ashrrev_i32_e32 v15, 31, v14
	v_readlane_b32 s50, v254, 30
	v_readlane_b32 s51, v254, 31
	ds_write2st64_b32 v1, v28, v29 offset1:2
	ds_write2st64_b32 v1, v26, v27 offset0:8 offset1:10
	ds_write2st64_b32 v1, v22, v23 offset0:16 offset1:18
	ds_write2st64_b32 v1, v18, v19 offset0:24 offset1:26
	ds_write2st64_b32 v1, v30, v31 offset0:4 offset1:6
	ds_write2st64_b32 v1, v24, v25 offset0:12 offset1:14
	ds_write2st64_b32 v1, v20, v21 offset0:20 offset1:22
	ds_write2st64_b32 v1, v16, v17 offset0:28 offset1:30
	v_lshl_add_u64 v[14:15], v[14:15], 2, s[50:51]
	s_waitcnt lgkmcnt(0)
	s_barrier
	global_load_dword v24, v[14:15], off
	ds_read2st64_b32 v[18:19], v35 offset0:32 offset1:64
	ds_read_b32 v25, v34
	ds_read_b32 v26, v35 offset:24576
	s_lshl_b64 s[6:7], s[6:7], 4
	v_lshl_add_u64 v[16:17], s[40:41], 2, v[6:7]
	v_lshl_add_u64 v[20:21], s[6:7], 0, v[2:3]
	s_waitcnt lgkmcnt(1)
	v_add_f32_e32 v18, v25, v18
	v_add_f32_e32 v18, v18, v19
	v_mad_u64_u32 v[22:23], s[0:1], v20, s15, v[16:17]
	s_waitcnt lgkmcnt(0)
	v_add_f32_e32 v18, v18, v26
	v_mad_i32_i24 v23, v21, s15, v23
	v_lshl_add_u64 v[20:21], s[6:7], 0, v[8:9]
	s_add_i32 s16, s16, s4
	v_readlane_b32 s48, v254, 28
	v_readlane_b32 s49, v254, 29
	s_cmpk_gt_i32 s16, 0x11f
	v_readlane_b32 s45, v254, 25
	v_readlane_b32 s46, v254, 26
	v_readlane_b32 s47, v254, 27
	v_readlane_b32 s52, v254, 32
	v_readlane_b32 s53, v254, 33
	v_readlane_b32 s54, v254, 34
	v_readlane_b32 s55, v254, 35
	v_readlane_b32 s56, v254, 36
	v_readlane_b32 s57, v254, 37
	v_readlane_b32 s58, v254, 38
	v_readlane_b32 s59, v254, 39
	s_waitcnt vmcnt(0)
	v_add_f32_e32 v18, v18, v24
	global_store_dword v[22:23], v18, off
	ds_read_b32 v25, v36
	ds_read_b32 v26, v37 offset:24576
	ds_read2st64_b32 v[18:19], v37 offset0:32 offset1:64
	v_mad_u64_u32 v[22:23], s[0:1], v20, s15, v[16:17]
	v_mad_i32_i24 v23, v21, s15, v23
	v_lshl_add_u64 v[20:21], s[6:7], 0, v[10:11]
	s_waitcnt lgkmcnt(0)
	v_add_f32_e32 v18, v25, v18
	v_add_f32_e32 v18, v18, v19
	v_add_f32_e32 v18, v18, v26
	v_add_f32_e32 v18, v18, v24
	global_store_dword v[22:23], v18, off
	ds_read_b32 v25, v38
	ds_read_b32 v26, v39 offset:24576
	ds_read2st64_b32 v[18:19], v39 offset0:32 offset1:64
	v_mad_u64_u32 v[22:23], s[0:1], v20, s15, v[16:17]
	v_mad_i32_i24 v23, v21, s15, v23
	s_waitcnt lgkmcnt(0)
	v_add_f32_e32 v18, v25, v18
	v_add_f32_e32 v18, v18, v19
	v_add_f32_e32 v18, v18, v26
	v_add_f32_e32 v18, v18, v24
	global_store_dword v[22:23], v18, off
	ds_read_b32 v21, v40
	ds_read_b32 v22, v41 offset:24576
	ds_read2st64_b32 v[14:15], v41 offset0:32 offset1:64
	v_lshl_add_u64 v[18:19], s[6:7], 0, v[12:13]
	v_mad_u64_u32 v[16:17], s[0:1], v18, s15, v[16:17]
	v_mad_i32_i24 v17, v19, s15, v17
	s_waitcnt lgkmcnt(0)
	v_add_f32_e32 v14, v21, v14
	v_add_f32_e32 v14, v14, v15
	v_add_f32_e32 v14, v14, v22
	v_add_f32_e32 v14, v14, v24
	global_store_dword v[16:17], v14, off
	s_barrier
	s_cbranch_scc0 .LBB0_118
